# MoBA: waves that skip a step delay their next-tile staging by a short sleep
# baseline (speedup 1.0000x reference)
.LBB0_148:
	s_cmp_ge_i32 s16, s48
	s_cselect_b64 s[8:9], -1, 0
	s_mov_b64 s[80:81], s[0:1]
	s_and_b64 vcc, exec, s[8:9]
	s_cbranch_vccnz .LBB0_151
	s_ashr_i32 s82, s51, 1
	s_sub_i32 s82, s47, s82
	s_lshl_b32 s82, 1, s82
	s_and_b32 s82, s82, s49
	s_cmp_lg_u32 s82, 0
	s_cbranch_scc1 .LBB0_151
	s_sleep 10
	s_xor_b32 s10, s15, 1
	s_mul_i32 s10, s10, 0x11000
	s_add_i32 s10, s10, 0
	v_add3_u32 v85, s10, v165, v216
	v_add3_u32 v84, s10, v0, v216
	v_add_u32_e32 v86, 0x8800, v85
	s_waitcnt vmcnt(7)
	ds_write_b128 v84, v[4:7]
	s_waitcnt vmcnt(6)
	ds_write2_b64 v86, v[8:9], v[10:11] offset1:2
	s_waitcnt vmcnt(5)
	ds_write_b128 v84, v[12:15] offset:8704
	v_add_u32_e32 v86, 0xa800, v85
	s_waitcnt vmcnt(4)
	ds_write2_b64 v86, v[16:17], v[18:19] offset0:64 offset1:66
	s_waitcnt vmcnt(3)
	ds_write_b128 v84, v[20:23] offset:17408
	v_add_u32_e32 v86, 0xc800, v85
	s_waitcnt vmcnt(2)
	ds_write2_b64 v86, v[24:25], v[26:27] offset0:128 offset1:130
	s_waitcnt vmcnt(1)
	ds_write_b128 v84, v[28:31] offset:26112
	v_add_u32_e32 v84, 0xe800, v85
	s_andn2_b64 vcc, exec, s[0:1]
	s_waitcnt vmcnt(0)
	ds_write2_b64 v84, v[32:33], v[34:35] offset0:192 offset1:194
	s_cbranch_vccnz .LBB0_151
	s_lshr_b32 s0, s14, 1
	s_sub_i32 s0, s47, s0
	s_lshl_b32 s1, s14, 7
	s_lshl_b32 s0, s0, 8
	s_and_b32 s1, s1, 0x80
	s_or_b32 s0, s0, s1
	s_ashr_i32 s1, s0, 31
	v_lshl_add_u64 v[4:5], v[140:141], 0, s[0:1]
	v_mov_b64_e32 v[6:7], s[88:89]
	v_lshl_add_u64 v[28:29], s[0:1], 1, v[118:119]
	v_mad_u64_u32 v[6:7], s[0:1], v4, s72, v[6:7]
	v_mad_i32_i24 v7, v5, s72, v7
	v_lshl_add_u64 v[4:5], v[6:7], 0, s[20:21]
	v_lshl_add_u64 v[30:31], v[4:5], 0, v[2:3]
	v_add_co_u32_e32 v4, vcc, s3, v30
	s_mov_b32 s0, 0x3d000
	s_nop 0
	v_addc_co_u32_e32 v5, vcc, 0, v31, vcc
	v_add_co_u32_e32 v12, vcc, s0, v30
	v_lshl_add_u64 v[8:9], v[28:29], 0, v[146:147]
	s_nop 0
	v_addc_co_u32_e32 v13, vcc, 0, v31, vcc
	v_add_co_u32_e32 v20, vcc, 0x79000, v30
	v_lshl_add_u64 v[16:17], v[28:29], 0, v[148:149]
	s_nop 0
	v_addc_co_u32_e32 v21, vcc, 0, v31, vcc
	v_add_co_u32_e32 v30, vcc, 0xb5000, v30
	v_lshl_add_u64 v[24:25], v[28:29], 0, v[150:151]
	s_nop 0
	v_addc_co_u32_e32 v31, vcc, 0, v31, vcc
	v_lshl_add_u64 v[32:33], v[28:29], 0, v[152:153]
	global_load_dwordx4 v[4:7], v[4:5], off offset:1024
	s_nop 0
	global_load_dwordx4 v[8:11], v[8:9], off
	s_nop 0
	global_load_dwordx4 v[12:15], v[12:13], off offset:1024
	s_nop 0
	global_load_dwordx4 v[16:19], v[16:17], off
	s_nop 0
	global_load_dwordx4 v[20:23], v[20:21], off offset:1024
	s_nop 0
	global_load_dwordx4 v[24:27], v[24:25], off
	s_nop 0
	global_load_dwordx4 v[28:31], v[30:31], off offset:1024
	s_nop 0
	global_load_dwordx4 v[32:35], v[32:33], off
